# Hyena N=16384 middle radix-4 loop: spectrum loads of both unrolled iterations issued together
# speedup vs baseline: 1.0044x; 1.0044x over previous
.LBB0_682:
	v_ashrrev_i32_e32 v1, 31, v0
	v_lshl_add_u64 v[76:77], v[0:1], 3, s[58:59]
	global_load_dwordx4 v[72:75], v[76:77], off offset:16
	s_nop 0
	global_load_dwordx4 v[76:79], v[76:77], off
	v_add_u32_e32 v196, 0x800, v0
	v_ashrrev_i32_e32 v197, 31, v196
	v_lshl_add_u64 v[196:197], v[196:197], 3, s[58:59]
	global_load_dwordx4 v[188:191], v[196:197], off offset:16
	global_load_dwordx4 v[192:195], v[196:197], off
	v_ashrrev_i32_e32 v1, 4, v0
	v_lshl_add_u32 v1, v1, 3, v3
	ds_read2_b64 v[80:83], v1 offset1:1
	ds_read2_b64 v[84:87], v1 offset0:2 offset1:3
	v_add_u32_e32 v2, 0x400, v2
	s_movk_i32 s8, 0xbff
	v_cmp_lt_i32_e32 vcc, s8, v2
	s_or_b64 s[6:7], vcc, s[6:7]
	s_waitcnt lgkmcnt(0)
	v_pk_add_f32 v[88:89], v[80:81], v[84:85]
	v_pk_add_f32 v[80:81], v[80:81], v[84:85] neg_lo:[0,1] neg_hi:[0,1]
	v_pk_add_f32 v[84:85], v[82:83], v[86:87]
	v_pk_add_f32 v[82:83], v[82:83], v[86:87] neg_lo:[0,1] neg_hi:[0,1]
	s_nop 0
	v_xor_b32_e32 v87, 0x80000000, v82
	v_mov_b32_e32 v86, v83
	v_pk_add_f32 v[82:83], v[88:89], v[84:85]
	v_pk_add_f32 v[90:91], v[80:81], v[86:87]
	v_pk_add_f32 v[80:81], v[80:81], v[86:87] neg_lo:[0,1] neg_hi:[0,1]
	v_pk_add_f32 v[84:85], v[88:89], v[84:85] neg_lo:[0,1] neg_hi:[0,1]
	s_waitcnt vmcnt(2)
	v_pk_mul_f32 v[86:87], v[76:77], v[82:83] op_sel:[1,1] op_sel_hi:[0,1]
	v_pk_fma_f32 v[88:89], v[76:77], v[82:83], v[86:87] neg_lo:[0,0,1] neg_hi:[0,0,1]
	v_pk_fma_f32 v[76:77], v[76:77], v[82:83], v[86:87] op_sel_hi:[1,0,1]
	s_nop 0
	v_mov_b32_e32 v89, v77
	v_pk_mul_f32 v[76:77], v[78:79], v[90:91] op_sel:[1,1] op_sel_hi:[0,1]
	v_pk_fma_f32 v[82:83], v[78:79], v[90:91], v[76:77] neg_lo:[0,0,1] neg_hi:[0,0,1]
	v_pk_fma_f32 v[76:77], v[78:79], v[90:91], v[76:77] op_sel_hi:[1,0,1]
	s_nop 0
	v_mov_b32_e32 v83, v77
	v_pk_mul_f32 v[76:77], v[72:73], v[84:85] op_sel:[1,1] op_sel_hi:[0,1]
	v_pk_fma_f32 v[78:79], v[72:73], v[84:85], v[76:77] neg_lo:[0,0,1] neg_hi:[0,0,1]
	v_pk_fma_f32 v[72:73], v[72:73], v[84:85], v[76:77] op_sel_hi:[1,0,1]
	s_nop 0
	v_mov_b32_e32 v79, v73
	v_pk_mul_f32 v[72:73], v[74:75], v[80:81] op_sel:[1,1] op_sel_hi:[0,1]
	v_pk_fma_f32 v[76:77], v[74:75], v[80:81], v[72:73] neg_lo:[0,0,1] neg_hi:[0,0,1]
	v_pk_fma_f32 v[72:73], v[74:75], v[80:81], v[72:73] op_sel_hi:[1,0,1]
	v_pk_add_f32 v[74:75], v[88:89], v[78:79] neg_lo:[0,1] neg_hi:[0,1]
	v_mov_b32_e32 v77, v73
	v_pk_add_f32 v[72:73], v[88:89], v[78:79]
	v_pk_add_f32 v[78:79], v[82:83], v[76:77]
	v_pk_add_f32 v[76:77], v[82:83], v[76:77] neg_lo:[0,1] neg_hi:[0,1]
	s_nop 0
	v_xor_b32_e32 v80, 0x80000000, v77
	v_mov_b32_e32 v81, v76
	v_pk_add_f32 v[82:83], v[74:75], v[80:81]
	v_pk_add_f32 v[74:75], v[74:75], v[80:81] neg_lo:[0,1] neg_hi:[0,1]
	v_add_u32_e32 v80, 0x800, v0
	v_pk_add_f32 v[76:77], v[72:73], v[78:79]
	v_ashrrev_i32_e32 v81, 31, v80
	v_pk_add_f32 v[72:73], v[72:73], v[78:79] neg_lo:[0,1] neg_hi:[0,1]
	ds_write2_b64 v1, v[76:77], v[82:83] offset1:1
	ds_write2_b64 v1, v[72:73], v[74:75] offset0:2 offset1:3
	v_lshl_add_u64 v[76:77], v[80:81], 3, s[58:59]
	v_ashrrev_i32_e32 v1, 4, v80
	v_lshl_add_u32 v1, v1, 3, v3
	v_add_u32_e32 v23, 0x4000, v1
	v_add_u32_e32 v1, 0x4010, v1
	ds_read2_b64 v[80:83], v23 offset1:1
	ds_read2_b64 v[84:87], v1 offset1:1
	v_add_u32_e32 v0, 0x1000, v0
	v_add_u32_e32 v3, 0x8000, v3
	s_waitcnt lgkmcnt(0)
	v_pk_add_f32 v[88:89], v[80:81], v[84:85]
	v_pk_add_f32 v[80:81], v[80:81], v[84:85] neg_lo:[0,1] neg_hi:[0,1]
	v_pk_add_f32 v[84:85], v[82:83], v[86:87]
	v_pk_add_f32 v[82:83], v[82:83], v[86:87] neg_lo:[0,1] neg_hi:[0,1]
	s_nop 0
	v_xor_b32_e32 v87, 0x80000000, v82
	v_mov_b32_e32 v86, v83
	v_pk_add_f32 v[82:83], v[88:89], v[84:85]
	v_pk_add_f32 v[90:91], v[80:81], v[86:87]
	v_pk_add_f32 v[80:81], v[80:81], v[86:87] neg_lo:[0,1] neg_hi:[0,1]
	v_pk_add_f32 v[84:85], v[88:89], v[84:85] neg_lo:[0,1] neg_hi:[0,1]
	s_waitcnt vmcnt(0)
	v_pk_mul_f32 v[86:87], v[192:193], v[82:83] op_sel:[1,1] op_sel_hi:[0,1]
	v_pk_fma_f32 v[88:89], v[192:193], v[82:83], v[86:87] neg_lo:[0,0,1] neg_hi:[0,0,1]
	v_pk_fma_f32 v[76:77], v[192:193], v[82:83], v[86:87] op_sel_hi:[1,0,1]
	s_nop 0
	v_mov_b32_e32 v89, v77
	v_pk_mul_f32 v[76:77], v[194:195], v[90:91] op_sel:[1,1] op_sel_hi:[0,1]
	v_pk_fma_f32 v[82:83], v[194:195], v[90:91], v[76:77] neg_lo:[0,0,1] neg_hi:[0,0,1]
	v_pk_fma_f32 v[76:77], v[194:195], v[90:91], v[76:77] op_sel_hi:[1,0,1]
	s_nop 0
	v_mov_b32_e32 v83, v77
	v_pk_mul_f32 v[76:77], v[188:189], v[84:85] op_sel:[1,1] op_sel_hi:[0,1]
	v_pk_fma_f32 v[78:79], v[188:189], v[84:85], v[76:77] neg_lo:[0,0,1] neg_hi:[0,0,1]
	v_pk_fma_f32 v[72:73], v[188:189], v[84:85], v[76:77] op_sel_hi:[1,0,1]
	s_nop 0
	v_mov_b32_e32 v79, v73
	v_pk_mul_f32 v[72:73], v[190:191], v[80:81] op_sel:[1,1] op_sel_hi:[0,1]
	v_pk_fma_f32 v[76:77], v[190:191], v[80:81], v[72:73] neg_lo:[0,0,1] neg_hi:[0,0,1]
	v_pk_fma_f32 v[72:73], v[190:191], v[80:81], v[72:73] op_sel_hi:[1,0,1]
	v_pk_add_f32 v[74:75], v[88:89], v[78:79] neg_lo:[0,1] neg_hi:[0,1]
	v_mov_b32_e32 v77, v73
	v_pk_add_f32 v[72:73], v[88:89], v[78:79]
	v_pk_add_f32 v[78:79], v[82:83], v[76:77]
	v_pk_add_f32 v[76:77], v[82:83], v[76:77] neg_lo:[0,1] neg_hi:[0,1]
	s_nop 0
	v_xor_b32_e32 v80, 0x80000000, v77
	v_mov_b32_e32 v81, v76
	v_pk_add_f32 v[76:77], v[72:73], v[78:79]
	v_pk_add_f32 v[82:83], v[74:75], v[80:81]
	v_pk_add_f32 v[72:73], v[72:73], v[78:79] neg_lo:[0,1] neg_hi:[0,1]
	v_pk_add_f32 v[74:75], v[74:75], v[80:81] neg_lo:[0,1] neg_hi:[0,1]
	ds_write2_b64 v23, v[76:77], v[82:83] offset1:1
	ds_write2_b64 v1, v[72:73], v[74:75] offset1:1
	s_andn2_b64 exec, exec, s[6:7]
	s_cbranch_execnz .LBB0_682
